# v054 + global attention softmax stabilised with a launch-wide upper bound c on the scores (Cauchy-Schwarz from q/k RMSNorm gains) when c<48: loop without per-tile row max/rescale check; online-max loo
# baseline (speedup 1.0000x reference)
; #define LAS __attribute__((address_space(3)))
; __global__ void __launch_bounds__(512, 2) mega_fwd(Args a) {
;     ...
;     for (int step2 = 0; step2 < 2 * NS; ++step2) {
;         const int step = step2 >> 1;
;         const bool dup_ = ((PH_DUP >> (step % N_PER)) & 1);
;         if ((step2 & 1) && !dup_) continue;
;         STEP_LOCALS
;         const int xl_good = __builtin_amdgcn_readfirstlane((int)((volatile LAS unsigned*)(lds + LDS_XB))[4]);
;         const int xl_x = __builtin_amdgcn_readfirstlane((int)((volatile LAS unsigned*)(lds + LDS_XB))[2]), xl_r = __builtin_amdgcn_readfirstlane((int)((volatile LAS unsigned*)(lds + LDS_XB))[3]);
;         const int cx = xl_good ? (xl_x + 8 * xl_r) : bx;
.LBB0_284:
	s_or_b64 exec, exec, s[0:1]
	s_ashr_i32 s1, s92, 31
	s_lshr_b32 s1, s1, 29
	s_add_i32 s1, s92, s1
	s_ashr_i32 s3, s1, 3
	s_and_b32 s1, s1, -8
	s_ashr_i32 s0, s14, 3
	s_sub_i32 s1, s92, s1
	s_mul_i32 s0, s0, s1
	s_add_i32 s3, s0, s3
	s_ashr_i32 s13, s14, 31
	s_lshl_b32 s50, s14, 1
	s_add_u32 s0, s6, 0x3c58a200
	s_addc_u32 s1, s7, 0
	v_writelane_b32 v254, s0, 4
	v_add_u32_e32 v0, 64, v149
	v_cmp_lt_i32_e32 vcc, v151, v0
	v_writelane_b32 v254, s1, 5
	s_add_u32 s0, s6, 0x3c58a400
	s_addc_u32 s1, s7, 0
	v_writelane_b32 v254, s0, 6
	v_cndmask_b32_e32 v1, v144, v151, vcc
	v_cmp_lt_i32_e32 vcc, v150, v0
	v_writelane_b32 v254, s1, 7
	s_add_u32 s0, s6, 0x3c58a500
	s_addc_u32 s1, s7, 0
	v_writelane_b32 v254, s0, 8
	v_lshlrev_b32_e32 v229, 2, v1
	v_cndmask_b32_e32 v1, v144, v150, vcc
	v_writelane_b32 v254, s1, 9
	s_add_u32 s0, s6, 0x3c58a600
	s_addc_u32 s1, s7, 0
	v_writelane_b32 v254, s0, 10
	v_cmp_lt_i32_e32 vcc, v148, v0
	v_lshlrev_b32_e32 v230, 2, v1
	v_writelane_b32 v254, s1, 11
	s_add_u32 s0, s6, 0x3c58a700
	s_addc_u32 s1, s7, 0
	v_writelane_b32 v254, s0, 12
	v_cndmask_b32_e32 v1, v144, v148, vcc
	v_cmp_lt_i32_e32 vcc, v147, v0
	v_writelane_b32 v254, s1, 13
	s_add_u32 s0, s6, 0x3c58a800
	s_addc_u32 s1, s7, 0
	v_writelane_b32 v254, s0, 14
	v_lshlrev_b32_e32 v231, 2, v1
	v_cndmask_b32_e32 v1, v144, v147, vcc
	v_writelane_b32 v254, s1, 15
	s_add_u32 s0, s6, 0x3c58a900
	s_addc_u32 s1, s7, 0
	v_writelane_b32 v254, s0, 16
	v_lshlrev_b32_e32 v232, 2, v1
	v_cmp_lt_i32_e32 vcc, v146, v0
	v_writelane_b32 v254, s1, 17
	s_add_u32 s0, s6, 0x3c58aa00
	s_addc_u32 s1, s7, 0
	v_writelane_b32 v254, s0, 18
	v_cndmask_b32_e32 v2, v144, v146, vcc
	v_cmp_lt_i32_e32 vcc, v145, v0
	v_writelane_b32 v254, s1, 19
	s_add_u32 s0, s6, 0x3c58ab00
	s_addc_u32 s1, s7, 0
	v_writelane_b32 v254, s0, 20
	v_cndmask_b32_e32 v0, v144, v145, vcc
	v_lshlrev_b32_e32 v234, 2, v0
	v_writelane_b32 v254, s1, 21
	s_add_u32 s0, s6, 0x3c58ac00
	s_addc_u32 s1, s7, 0
	v_writelane_b32 v254, s0, 22
	s_mul_i32 s2, s15, s14
	v_lshlrev_b32_e32 v233, 2, v2
	v_writelane_b32 v254, s1, 23
	s_add_u32 s0, s6, 0x3c58ad00
	s_addc_u32 s1, s7, 0
	v_writelane_b32 v254, s0, 24
	s_mov_b32 s65, 0
	s_movk_i32 s60, 0x100
	v_writelane_b32 v254, s1, 25
	s_add_u32 s0, s6, 0x3c58ae00
	s_addc_u32 s1, s7, 0
	v_writelane_b32 v254, s0, 26
	s_movk_i32 s77, 0x90
	s_movk_i32 s78, 0xffe0
	v_writelane_b32 v254, s1, 27
	s_add_u32 s0, s6, 0x3c58af00
	s_addc_u32 s1, s7, 0
	v_writelane_b32 v254, s0, 28
	v_mov_b32_e32 v235, 0x358637bd
	s_movk_i32 s79, 0x1600
	v_writelane_b32 v254, s1, 29
	s_add_u32 s0, s6, 0x3c58b000
	s_addc_u32 s1, s7, 0
	v_writelane_b32 v254, s0, 30
	s_mov_b32 s22, 0xf800000
	v_mov_b32_e32 v238, 0x260
	v_writelane_b32 v254, s1, 31
	s_add_u32 s0, s6, 0x3c58b100
	s_addc_u32 s1, s7, 0
	v_writelane_b32 v254, s0, 32
	s_movk_i32 s62, 0x110
	v_mov_b32_e32 v241, 0x2000
	v_writelane_b32 v254, s1, 33
	s_add_u32 s0, s6, 0x3c58b200
	s_addc_u32 s1, s7, 0
	v_writelane_b32 v254, s0, 34
	v_mov_b64_e32 v[196:197], 0x200
	v_mov_b64_e32 v[198:199], 0x1ff
	v_writelane_b32 v254, s1, 35
	s_add_u32 s0, s6, 0x3c58b300
	s_addc_u32 s1, s7, 0
	v_writelane_b32 v254, s0, 36
	v_mov_b64_e32 v[250:251], 0xb00
	v_mov_b64_e32 v[202:203], 0xaff
	v_writelane_b32 v254, s1, 37
	s_add_u32 s0, s6, 0x3c58d400
	s_addc_u32 s1, s7, 0
	v_writelane_b32 v254, s0, 38
	v_mov_b32_e32 v239, 0xa0000
	s_mov_b32 s25, 0
	v_writelane_b32 v254, s1, 39
	s_add_u32 s0, s6, 0x3c58d500
	s_addc_u32 s1, s7, 0
	v_writelane_b32 v254, s0, 40
	s_mov_b64 s[68:69], 0x80
	s_mov_b64 s[80:81], 0x20000
	v_writelane_b32 v254, s1, 41
	s_and_b64 s[0:1], s[8:9], exec
	s_cselect_b32 s3, s3, s92
	s_lshl_b32 s0, s3, 3
	s_cmpk_lt_i32 s3, 0x400
	v_writelane_b32 v254, s0, 42
	s_cselect_b64 s[0:1], -1, 0
	v_writelane_b32 v254, s0, 43
	s_cmpk_lt_i32 s3, 0x200
	s_mov_b64 s[82:83], 0x1000
	v_writelane_b32 v254, s1, 44
	s_cselect_b64 s[0:1], -1, 0
	v_writelane_b32 v254, s0, 45
	s_waitcnt lgkmcnt(0)
	s_barrier
; #define INP(i) ldsptr(lds, (i))
; __global__ void __launch_bounds__(512, 2) mega_fwd(Args a) {
;     ...
;                 const gfloat* qn_att = INP(I_QN);
;                 for (int u = vcu; ATT_EN(0) && u < (CH / 256) * 8; u += G) {
;                     const int qb = u % NQB, g4 = (u / NQB) % 4, kvh = (u / NQB / 4) % 2, seq = u / (NQB * 8), head = kvh * 4 + g4;
;                     const size_t tokq = (size_t)seq * S_ + (size_t)qb * 256;
;                     attn_unit<64, 0>(lds, tid, proj + tokq * PROJ + 64 * head, PROJ, proj + (size_t)seq * S_ * PROJ + 512 + 64 * kvh, PROJ,
;                                      vta + ((size_t)(seq * 2 + kvh) * 64) * S_, S_, yb3 + tokq * 512 + 64 * head, 512, 0, S_ / 64,
;                                      0.125f * LOG2E, qb * 256, nullptr, -1e30f, 0.f, qn_att, rope);
	v_writelane_b32 v254, s1, 46
	s_abs_i32 s0, s50
	v_cvt_f32_u32_e32 v1, s0
	s_mul_i32 s1, s2, s33
	v_writelane_b32 v254, s1, 47
	s_sub_i32 s1, 0, s0
	v_rcp_iflag_f32_e32 v1, v1
	s_movk_i32 s33, 0x2800
	v_mul_f32_e32 v0, 0x4f7ffffe, v1
	v_cvt_u32_f32_e32 v0, v0
	v_mov_b32_e32 v1, 0
	v_readfirstlane_b32 s2, v0
	s_mul_i32 s1, s1, s2
	s_mul_hi_u32 s1, s2, s1
	s_add_i32 s2, s2, s1
	s_lshr_b32 s1, s2, 20
	s_mul_i32 s1, s1, s0
	s_sub_i32 s1, 0x1000, s1
	s_sub_i32 s2, s1, s0
	s_cmp_ge_u32 s1, s0
	s_cselect_b32 s1, s2, s1
	s_sub_i32 s2, s1, s0
	s_cmp_ge_u32 s1, s0
	s_cselect_b32 s0, s2, s1
	s_cmp_lg_u32 s0, 0
	s_cselect_b64 s[0:1], -1, 0
	v_writelane_b32 v254, s0, 48
	s_lshl_b32 s12, s14, 4
	s_add_i32 s61, 0, 0x21460
	v_writelane_b32 v254, s1, 49
	s_lshl_b32 s0, s3, 6
	v_writelane_b32 v254, s0, 50
	s_lshl_b32 s0, s14, 6
	v_writelane_b32 v254, s0, 51
	v_writelane_b32 v254, s3, 52
	s_lshl_b32 s0, s3, 7
	v_writelane_b32 v254, s0, 53
	s_add_i32 s0, 0, 0x214b8
	v_writelane_b32 v254, s0, 54
	s_add_i32 s0, 0, 0x21510
	v_writelane_b32 v254, s0, 55
	s_add_i32 s0, 0, 0x21508
	v_writelane_b32 v254, s0, 56
	s_add_i32 s0, 0, 0x2150c
	v_writelane_b32 v254, s0, 57
	s_add_i32 s0, 0, 0x214b0
	v_writelane_b32 v254, s0, 58
	s_add_i32 s0, 0, 0x20000
	v_writelane_b32 v254, s0, 59
	s_add_i32 s0, 0, 0x21450
	v_writelane_b32 v254, s0, 60
	s_add_i32 s0, 0, 0x1b600
	v_writelane_b32 v254, s0, 61
	s_add_i32 s0, 0, 0x21458
	v_writelane_b32 v254, s0, 62
	s_add_i32 s0, 0, 0x21428
	v_writelane_b32 v254, s0, 63
	s_add_i32 s0, 0, 0x21500
	v_writelane_b32 v255, s0, 0
	s_add_i32 s0, 0, 0x21504
	v_writelane_b32 v255, s0, 1
	v_writelane_b32 v255, s92, 2
	v_writelane_b32 v255, s12, 3
	v_writelane_b32 v255, s61, 4
	s_lshl_b32 s19, s14, 7
	s_add_i32 s76, 0, 0x21000
	v_writelane_b32 v255, s50, 5
	v_mov_b32_e32 v246, 0x21450
	ds_read_b128 v[246:249], v246
	v_and_b32_e32 v252, 63, v228
	v_lshlrev_b32_e32 v252, 2, v252
	v_mov_b32_e32 v253, 0
	s_waitcnt lgkmcnt(0)
	v_lshl_add_u64 v[246:247], v[246:247], 0, v[252:253]
	v_lshl_add_u64 v[248:249], v[248:249], 0, v[252:253]
	global_load_dword v246, v[246:247], off
	global_load_dword v248, v[248:249], off
	s_waitcnt vmcnt(0)
	v_and_b32_e32 v246, 0x7fffffff, v246
	v_and_b32_e32 v248, 0x7fffffff, v248
	v_xor_b32_e32 v253, 4, v252
	ds_bpermute_b32 v247, v253, v246
	ds_bpermute_b32 v249, v253, v248
	s_waitcnt lgkmcnt(0)
	v_max_f32_e32 v246, v246, v247
	v_max_f32_e32 v248, v248, v249
	v_xor_b32_e32 v253, 8, v252
	ds_bpermute_b32 v247, v253, v246
	ds_bpermute_b32 v249, v253, v248
	s_waitcnt lgkmcnt(0)
	v_max_f32_e32 v246, v246, v247
	v_max_f32_e32 v248, v248, v249
	v_xor_b32_e32 v253, 16, v252
	ds_bpermute_b32 v247, v253, v246
	ds_bpermute_b32 v249, v253, v248
	s_waitcnt lgkmcnt(0)
	v_max_f32_e32 v246, v246, v247
	v_max_f32_e32 v248, v248, v249
	v_xor_b32_e32 v253, 32, v252
	ds_bpermute_b32 v247, v253, v246
	ds_bpermute_b32 v249, v253, v248
	s_waitcnt lgkmcnt(0)
	v_max_f32_e32 v246, v246, v247
	v_max_f32_e32 v248, v248, v249
	v_xor_b32_e32 v253, 64, v252
	ds_bpermute_b32 v247, v253, v246
	ds_bpermute_b32 v249, v253, v248
	s_waitcnt lgkmcnt(0)
	v_max_f32_e32 v246, v246, v247
	v_max_f32_e32 v248, v248, v249
	v_xor_b32_e32 v253, 128, v252
	ds_bpermute_b32 v247, v253, v246
	ds_bpermute_b32 v249, v253, v248
	s_waitcnt lgkmcnt(0)
	v_max_f32_e32 v246, v246, v247
	v_max_f32_e32 v248, v248, v249
	v_mul_f32_e32 v246, v246, v248
	v_mul_f32_e32 v246, 0x414fbf83, v246
	s_nop 1
	v_readfirstlane_b32 s0, v246
	s_nop 3
	v_writelane_b32 v255, s0, 20
	s_branch .LBB0_289

.LBB0_496:
	v_ashrrev_i32_e32 v191, 31, v190
	v_lshlrev_b32_e32 v207, 2, v168
	s_waitcnt lgkmcnt(7)
	v_mfma_f32_32x32x16_bf16 v[66:81], v[162:165], v[130:133], v[34:49]
	v_exp_f32_e32 v65, v98
	v_exp_f32_e32 v162, v99
	s_nop 0
	v_cvt_pk_bf16_f32 v98, v65, v162
	v_add_f32_e32 v65, 0, v65
	v_add_f32_e32 v65, v162, v65
	s_waitcnt lgkmcnt(5)
	v_mfma_f32_32x32x16_bf16 v[34:49], v[158:161], v[130:133], v[34:49]
	v_exp_f32_e32 v158, v100
	v_exp_f32_e32 v159, v101
	v_add_f32_e32 v65, v158, v65
	v_cvt_pk_bf16_f32 v99, v158, v159
	v_add_f32_e32 v65, v159, v65
	v_mfma_f32_32x32x16_bf16 v[66:81], v[154:157], v[134:137], v[66:81]
	v_exp_f32_e32 v154, v102
	v_exp_f32_e32 v155, v103
	v_add_f32_e32 v65, v154, v65
	v_cvt_pk_bf16_f32 v100, v154, v155
	v_add_f32_e32 v65, v155, v65
	s_waitcnt lgkmcnt(3)
	v_mfma_f32_32x32x16_bf16 v[66:81], v[126:129], v[138:141], v[66:81]
	v_exp_f32_e32 v104, v104
	v_exp_f32_e32 v105, v105
	v_add_f32_e32 v65, v104, v65
	v_cvt_pk_bf16_f32 v101, v104, v105
	v_add_f32_e32 v65, v105, v65
	s_waitcnt lgkmcnt(2)
	v_mfma_f32_32x32x16_bf16 v[66:81], v[122:125], v[142:145], v[66:81]
	v_exp_f32_e32 v106, v106
	v_exp_f32_e32 v107, v107
	s_nop 0
	v_cvt_pk_bf16_f32 v102, v106, v107
	v_exp_f32_e32 v108, v108
	v_mfma_f32_32x32x16_bf16 v[34:49], v[60:63], v[134:137], v[34:49]
	v_exp_f32_e32 v109, v109
	v_add_f32_e32 v60, v106, v65
	v_add_f32_e32 v60, v107, v60
	v_add_f32_e32 v60, v108, v60
	v_cvt_pk_bf16_f32 v103, v108, v109
	v_exp_f32_e32 v110, v110
	v_exp_f32_e32 v111, v111
	s_waitcnt lgkmcnt(1)
	v_mfma_f32_32x32x16_bf16 v[34:49], v[56:59], v[138:141], v[34:49]
	v_add_f32_e32 v60, v109, v60
	v_add_f32_e32 v60, v110, v60
	v_cvt_pk_bf16_f32 v104, v110, v111
	v_exp_f32_e32 v112, v112
	v_exp_f32_e32 v162, v113
	v_add_f32_e32 v60, v111, v60
	v_add_f32_e32 v65, v112, v60
	v_cvt_pk_bf16_f32 v105, v112, v162
	s_setprio 0
	ds_read_b128 v[56:59], v64 offset:27648
	ds_read_b128 v[60:63], v64 offset:27680
	ds_read_b128 v[106:109], v64 offset:27712
	ds_read_b128 v[110:113], v64 offset:27744
	ds_read_b128 v[122:125], v64 offset:32256
	ds_read_b128 v[126:129], v64 offset:32288
	ds_read_b128 v[154:157], v64 offset:32320
	ds_read_b128 v[158:161], v64 offset:32352
	v_add_f32_e32 v64, v162, v65
	v_exp_f32_e32 v65, v82
	v_exp_f32_e32 v82, v83
	v_exp_f32_e32 v83, v84
	v_exp_f32_e32 v84, v85
	v_add_f32_e32 v64, v65, v64
	v_exp_f32_e32 v85, v86
	v_add_f32_e32 v64, v82, v64
	v_exp_f32_e32 v86, v87
	v_add_f32_e32 v64, v83, v64
	v_exp_f32_e32 v87, v88
	v_add_f32_e32 v64, v84, v64
	v_exp_f32_e32 v88, v89
	v_add_f32_e32 v64, v85, v64
	v_exp_f32_e32 v89, v90
	v_add_f32_e32 v64, v86, v64
	v_exp_f32_e32 v90, v91
	v_add_f32_e32 v64, v87, v64
	v_exp_f32_e32 v91, v92
	v_add_f32_e32 v64, v88, v64
	v_exp_f32_e32 v92, v93
	v_add_f32_e32 v64, v89, v64
	v_exp_f32_e32 v93, v94
	v_add_f32_e32 v64, v90, v64
	v_exp_f32_e32 v94, v95
	v_add_f32_e32 v64, v91, v64
	v_exp_f32_e32 v95, v96
	v_add_f32_e32 v64, v92, v64
	v_exp_f32_e32 v96, v97
	v_add_f32_e32 v64, v93, v64
	v_add_f32_e32 v64, v94, v64
	v_add_f32_e32 v64, v95, v64
	v_add_f32_e32 v64, v96, v64
	v_cvt_pk_bf16_f32 v82, v65, v82
	v_cvt_pk_bf16_f32 v83, v83, v84
	v_cvt_pk_bf16_f32 v84, v85, v86
	v_cvt_pk_bf16_f32 v85, v87, v88
	v_cvt_pk_bf16_f32 v86, v89, v90
	v_cvt_pk_bf16_f32 v87, v91, v92
	v_cvt_pk_bf16_f32 v88, v93, v94
	v_cvt_pk_bf16_f32 v89, v95, v96
	s_setprio 1
	s_waitcnt lgkmcnt(7)
	v_mfma_f32_32x32x16_bf16 v[18:33], v[56:59], v[98:101], v[18:33]
	v_add_f32_e32 v210, v50, v64
	s_waitcnt lgkmcnt(3)
	v_mfma_f32_32x32x16_bf16 v[2:17], v[122:125], v[98:101], v[2:17]
	v_mfma_f32_32x32x16_bf16 v[18:33], v[60:63], v[102:105], v[18:33]
	s_waitcnt lgkmcnt(2)
	v_mfma_f32_32x32x16_bf16 v[2:17], v[126:129], v[102:105], v[2:17]
	v_mfma_f32_32x32x16_bf16 v[18:33], v[106:109], v[82:85], v[18:33]
	s_waitcnt lgkmcnt(1)
	v_mfma_f32_32x32x16_bf16 v[2:17], v[154:157], v[82:85], v[2:17]
	v_mfma_f32_32x32x16_bf16 v[18:33], v[110:113], v[86:89], v[18:33]
	s_waitcnt lgkmcnt(0)
	v_mfma_f32_32x32x16_bf16 v[2:17], v[158:161], v[86:89], v[2:17]
	v_mfma_f32_32x32x16_bf16 v[34:49], v[52:55], v[142:145], v[34:49]
	s_setprio 0
	s_movk_i32 s2, 0x4800
	s_mov_b32 s3, 0
	s_mov_b32 s0, 0x9000
	s_mov_b32 s10, 6
	v_mov_b32_e32 v50, v51
	v_mov_b32_e32 v52, v51
	v_mov_b32_e32 v53, v51
	v_mov_b32_e32 v54, v51
	v_mov_b32_e32 v55, v51
	v_mov_b32_e32 v56, v51
	v_mov_b32_e32 v57, v51
	v_mov_b32_e32 v58, v51
	v_mov_b32_e32 v59, v51
	v_mov_b32_e32 v60, v51
	v_mov_b32_e32 v61, v51
	v_mov_b32_e32 v62, v51
	v_mov_b32_e32 v63, v51
	v_mov_b32_e32 v64, v51
	v_mov_b32_e32 v65, v51
	s_waitcnt vmcnt(3)
	ds_write_b128 v169, v[114:117]
	s_waitcnt vmcnt(2)
	ds_write_b128 v170, v[118:121] offset:9216
	v_readlane_b32 s1, v255, 20
	s_nop 3
	s_cmp_lt_u32 s1, 0x42400000
	s_cbranch_scc0 .Lattn_online_pre
	v_sub_f32_e32 v50, s1, v206
	v_exp_f32_e64 v52, -v50
	v_mov_b32_e32 v206, s1
	v_pk_add_f32 v[66:67], v[66:67], v[50:51] op_sel_hi:[1,0] neg_lo:[0,1] neg_hi:[0,1]
	v_pk_add_f32 v[68:69], v[68:69], v[50:51] op_sel_hi:[1,0] neg_lo:[0,1] neg_hi:[0,1]
	v_pk_add_f32 v[70:71], v[70:71], v[50:51] op_sel_hi:[1,0] neg_lo:[0,1] neg_hi:[0,1]
	v_pk_add_f32 v[72:73], v[72:73], v[50:51] op_sel_hi:[1,0] neg_lo:[0,1] neg_hi:[0,1]
	v_pk_add_f32 v[74:75], v[74:75], v[50:51] op_sel_hi:[1,0] neg_lo:[0,1] neg_hi:[0,1]
	v_pk_add_f32 v[76:77], v[76:77], v[50:51] op_sel_hi:[1,0] neg_lo:[0,1] neg_hi:[0,1]
	v_pk_add_f32 v[78:79], v[78:79], v[50:51] op_sel_hi:[1,0] neg_lo:[0,1] neg_hi:[0,1]
	v_pk_add_f32 v[80:81], v[80:81], v[50:51] op_sel_hi:[1,0] neg_lo:[0,1] neg_hi:[0,1]
	v_pk_add_f32 v[34:35], v[34:35], v[50:51] op_sel_hi:[1,0] neg_lo:[0,1] neg_hi:[0,1]
	v_pk_add_f32 v[36:37], v[36:37], v[50:51] op_sel_hi:[1,0] neg_lo:[0,1] neg_hi:[0,1]
	v_pk_add_f32 v[38:39], v[38:39], v[50:51] op_sel_hi:[1,0] neg_lo:[0,1] neg_hi:[0,1]
	v_pk_add_f32 v[40:41], v[40:41], v[50:51] op_sel_hi:[1,0] neg_lo:[0,1] neg_hi:[0,1]
	v_pk_add_f32 v[42:43], v[42:43], v[50:51] op_sel_hi:[1,0] neg_lo:[0,1] neg_hi:[0,1]
	v_pk_add_f32 v[44:45], v[44:45], v[50:51] op_sel_hi:[1,0] neg_lo:[0,1] neg_hi:[0,1]
	v_pk_add_f32 v[46:47], v[46:47], v[50:51] op_sel_hi:[1,0] neg_lo:[0,1] neg_hi:[0,1]
	v_pk_add_f32 v[48:49], v[48:49], v[50:51] op_sel_hi:[1,0] neg_lo:[0,1] neg_hi:[0,1]
	v_pk_mul_f32 v[2:3], v[2:3], v[52:53] op_sel_hi:[1,0]
	v_pk_mul_f32 v[4:5], v[4:5], v[52:53] op_sel_hi:[1,0]
	v_pk_mul_f32 v[6:7], v[6:7], v[52:53] op_sel_hi:[1,0]
	v_pk_mul_f32 v[8:9], v[8:9], v[52:53] op_sel_hi:[1,0]
	v_pk_mul_f32 v[10:11], v[10:11], v[52:53] op_sel_hi:[1,0]
	v_pk_mul_f32 v[12:13], v[12:13], v[52:53] op_sel_hi:[1,0]
	v_pk_mul_f32 v[14:15], v[14:15], v[52:53] op_sel_hi:[1,0]
	v_pk_mul_f32 v[16:17], v[16:17], v[52:53] op_sel_hi:[1,0]
	v_pk_mul_f32 v[18:19], v[18:19], v[52:53] op_sel_hi:[1,0]
	v_pk_mul_f32 v[20:21], v[20:21], v[52:53] op_sel_hi:[1,0]
	v_pk_mul_f32 v[22:23], v[22:23], v[52:53] op_sel_hi:[1,0]
	v_pk_mul_f32 v[24:25], v[24:25], v[52:53] op_sel_hi:[1,0]
	v_pk_mul_f32 v[26:27], v[26:27], v[52:53] op_sel_hi:[1,0]
	v_pk_mul_f32 v[28:29], v[28:29], v[52:53] op_sel_hi:[1,0]
	v_pk_mul_f32 v[30:31], v[30:31], v[52:53] op_sel_hi:[1,0]
	v_pk_mul_f32 v[32:33], v[32:33], v[52:53] op_sel_hi:[1,0]
	v_mul_f32_e32 v210, v210, v52
	v_xor_b32_e32 v50, 0x80000000, v206
	v_mov_b32_e32 v51, v50
	v_mov_b32_e32 v52, v50
	v_mov_b32_e32 v53, v50
	v_mov_b32_e32 v54, v50
	v_mov_b32_e32 v55, v50
	v_mov_b32_e32 v56, v50
	v_mov_b32_e32 v57, v50
	v_mov_b32_e32 v58, v50
	v_mov_b32_e32 v59, v50
	v_mov_b32_e32 v60, v50
	v_mov_b32_e32 v61, v50
	v_mov_b32_e32 v62, v50
	v_mov_b32_e32 v63, v50
	v_mov_b32_e32 v64, v50
	v_mov_b32_e32 v65, v50
